# flat barrier release + per-XCC generation atomic removed from the leader path (nobody reads it any more)
# speedup vs baseline: 1.0055x; 1.0055x over previous
.LBB0_72:
	s_or_b64 exec, exec, s[6:7]
	s_mov_b64 s[6:7], exec
	v_mbcnt_lo_u32_b32 v0, s6, 0
	v_mbcnt_hi_u32_b32 v0, s7, v0
	v_cmp_eq_u32_e32 vcc, 0, v0
	s_waitcnt vmcnt(0)
	buffer_inv sc1
	s_and_saveexec_b64 s[8:9], vcc
	s_cbranch_execz .LBB0_74
	s_bcnt1_i32_b64 s6, s[6:7]
	v_mov_b32_e32 v0, 0x2000
	v_mov_b32_e32 v1, s6
.LBB0_74:
	s_or_b64 exec, exec, s[8:9]
	s_waitcnt vmcnt(0)

.LBB0_195:
	s_or_b64 exec, exec, s[4:5]
	s_mov_b64 s[4:5], exec
	v_mbcnt_lo_u32_b32 v0, s4, 0
	v_mbcnt_hi_u32_b32 v0, s5, v0
	v_cmp_eq_u32_e32 vcc, 0, v0
	s_waitcnt vmcnt(0)
	buffer_inv sc1
	s_and_saveexec_b64 s[8:9], vcc
	s_cbranch_execz .LBB0_197
	s_bcnt1_i32_b64 s4, s[4:5]
	v_mov_b32_e32 v0, 0x2000
	v_mov_b32_e32 v1, s4
.LBB0_197:
	s_or_b64 exec, exec, s[8:9]
	s_waitcnt vmcnt(0)

.LBB0_266:
	s_or_b64 exec, exec, s[6:7]
	s_mov_b64 s[6:7], exec
	v_mbcnt_lo_u32_b32 v0, s6, 0
	v_mbcnt_hi_u32_b32 v0, s7, v0
	v_cmp_eq_u32_e32 vcc, 0, v0
	s_waitcnt vmcnt(0)
	buffer_inv sc1
	s_and_saveexec_b64 s[8:9], vcc
	s_cbranch_execz .LBB0_268
	s_bcnt1_i32_b64 s6, s[6:7]
	v_mov_b32_e32 v0, 0x2000
	v_mov_b32_e32 v1, s6
.LBB0_268:
	s_or_b64 exec, exec, s[8:9]
	s_waitcnt vmcnt(0)

.LBB0_337:
	s_or_b64 exec, exec, s[4:5]
	s_mov_b64 s[4:5], exec
	v_mbcnt_lo_u32_b32 v0, s4, 0
	v_mbcnt_hi_u32_b32 v0, s5, v0
	v_cmp_eq_u32_e32 vcc, 0, v0
	s_waitcnt vmcnt(0)
	buffer_inv sc1
	s_and_saveexec_b64 s[6:7], vcc
	s_cbranch_execz .LBB0_339
	s_bcnt1_i32_b64 s4, s[4:5]
	v_mov_b32_e32 v0, 0x2000
	v_mov_b32_e32 v1, s4
.LBB0_339:
	s_or_b64 exec, exec, s[6:7]
	s_waitcnt vmcnt(0)

.LBB0_414:
	s_or_b64 exec, exec, s[6:7]
	s_mov_b64 s[6:7], exec
	v_mbcnt_lo_u32_b32 v0, s6, 0
	v_mbcnt_hi_u32_b32 v0, s7, v0
	v_cmp_eq_u32_e32 vcc, 0, v0
	s_waitcnt vmcnt(0)
	buffer_inv sc1
	s_and_saveexec_b64 s[8:9], vcc
	s_cbranch_execz .LBB0_416
	s_bcnt1_i32_b64 s6, s[6:7]
	v_mov_b32_e32 v0, 0x2000
	v_mov_b32_e32 v1, s6
.LBB0_416:
	s_or_b64 exec, exec, s[8:9]
	s_waitcnt vmcnt(0)

.LBB0_491:
	s_or_b64 exec, exec, s[4:5]
	s_mov_b64 s[4:5], exec
	v_mbcnt_lo_u32_b32 v0, s4, 0
	v_mbcnt_hi_u32_b32 v0, s5, v0
	v_cmp_eq_u32_e32 vcc, 0, v0
	s_waitcnt vmcnt(0)
	buffer_inv sc1
	s_and_saveexec_b64 s[6:7], vcc
	s_cbranch_execz .LBB0_493
	s_bcnt1_i32_b64 s4, s[4:5]
	v_mov_b32_e32 v0, 0x2000
	v_mov_b32_e32 v1, s4
.LBB0_493:
	s_or_b64 exec, exec, s[6:7]
	s_waitcnt vmcnt(0)

.LBB0_706:
	s_or_b64 exec, exec, s[6:7]
	s_mov_b64 s[6:7], exec
	v_mbcnt_lo_u32_b32 v0, s6, 0
	v_mbcnt_hi_u32_b32 v0, s7, v0
	v_cmp_eq_u32_e32 vcc, 0, v0
	s_waitcnt vmcnt(0)
	buffer_inv sc1
	s_and_saveexec_b64 s[8:9], vcc
	s_cbranch_execz .LBB0_708
	s_bcnt1_i32_b64 s6, s[6:7]
	v_mov_b32_e32 v0, 0x2000
	v_mov_b32_e32 v1, s6
.LBB0_708:
	s_or_b64 exec, exec, s[8:9]
	s_waitcnt vmcnt(0)

.LBB0_777:
	s_or_b64 exec, exec, s[4:5]
	s_mov_b64 s[4:5], exec
	v_mbcnt_lo_u32_b32 v0, s4, 0
	v_mbcnt_hi_u32_b32 v0, s5, v0
	v_cmp_eq_u32_e32 vcc, 0, v0
	s_waitcnt vmcnt(0)
	buffer_inv sc1
	s_and_saveexec_b64 s[8:9], vcc
	s_cbranch_execz .LBB0_779
	s_bcnt1_i32_b64 s4, s[4:5]
	v_mov_b32_e32 v0, 0x2000
	v_mov_b32_e32 v1, s4
.LBB0_779:
	s_or_b64 exec, exec, s[8:9]
	s_waitcnt vmcnt(0)

.LBB0_886:
	s_or_b64 exec, exec, s[6:7]
	s_mov_b64 s[6:7], exec
	v_mbcnt_lo_u32_b32 v0, s6, 0
	v_mbcnt_hi_u32_b32 v0, s7, v0
	v_cmp_eq_u32_e32 vcc, 0, v0
	s_waitcnt vmcnt(0)
	buffer_inv sc1
	s_and_saveexec_b64 s[8:9], vcc
	s_cbranch_execz .LBB0_888
	s_bcnt1_i32_b64 s6, s[6:7]
	v_mov_b32_e32 v0, 0x2000
	v_mov_b32_e32 v1, s6
.LBB0_888:
	s_or_b64 exec, exec, s[8:9]
	s_waitcnt vmcnt(0)

.LBB0_961:
	s_or_b64 exec, exec, s[6:7]
	s_mov_b64 s[6:7], exec
	v_mbcnt_lo_u32_b32 v0, s6, 0
	v_mbcnt_hi_u32_b32 v0, s7, v0
	v_cmp_eq_u32_e32 vcc, 0, v0
	s_waitcnt vmcnt(0)
	buffer_inv sc1
	s_and_saveexec_b64 s[8:9], vcc
	s_cbranch_execz .LBB0_963
	s_bcnt1_i32_b64 s6, s[6:7]
	v_mov_b32_e32 v0, 0x2000
	v_mov_b32_e32 v1, s6
.LBB0_963:
	s_or_b64 exec, exec, s[8:9]
	s_waitcnt vmcnt(0)

.LBB0_1032:
	s_or_b64 exec, exec, s[6:7]
	s_mov_b64 s[6:7], exec
	v_mbcnt_lo_u32_b32 v0, s6, 0
	v_mbcnt_hi_u32_b32 v0, s7, v0
	v_cmp_eq_u32_e32 vcc, 0, v0
	s_waitcnt vmcnt(0)
	buffer_inv sc1
	s_and_saveexec_b64 s[8:9], vcc
	s_cbranch_execz .LBB0_1034
	s_bcnt1_i32_b64 s6, s[6:7]
	v_mov_b32_e32 v0, 0x2000
	v_mov_b32_e32 v1, s6
.LBB0_1034:
	s_or_b64 exec, exec, s[8:9]
	s_waitcnt vmcnt(0)

.LBB0_1103:
	s_or_b64 exec, exec, s[6:7]
	s_mov_b64 s[6:7], exec
	v_mbcnt_lo_u32_b32 v0, s6, 0
	v_mbcnt_hi_u32_b32 v0, s7, v0
	v_cmp_eq_u32_e32 vcc, 0, v0
	s_waitcnt vmcnt(0)
	buffer_inv sc1
	s_and_saveexec_b64 s[8:9], vcc
	s_cbranch_execz .LBB0_1105
	s_bcnt1_i32_b64 s6, s[6:7]
	v_mov_b32_e32 v0, 0x2000
	v_mov_b32_e32 v1, s6
.LBB0_1105:
	s_or_b64 exec, exec, s[8:9]
	s_waitcnt vmcnt(0)

.LBB0_1168:
	s_or_b64 exec, exec, s[6:7]
	s_mov_b64 s[6:7], exec
	v_mbcnt_lo_u32_b32 v0, s6, 0
	v_mbcnt_hi_u32_b32 v0, s7, v0
	v_cmp_eq_u32_e32 vcc, 0, v0
	s_waitcnt vmcnt(0)
	buffer_inv sc1
	s_and_saveexec_b64 s[8:9], vcc
	s_cbranch_execz .LBB0_1170
	s_bcnt1_i32_b64 s6, s[6:7]
	v_mov_b32_e32 v0, 0x2000
	v_mov_b32_e32 v1, s6
.LBB0_1170:
	s_or_b64 exec, exec, s[8:9]
	s_waitcnt vmcnt(0)

.LBB0_1239:
	s_or_b64 exec, exec, s[6:7]
	s_mov_b64 s[6:7], exec
	v_mbcnt_lo_u32_b32 v0, s6, 0
	v_mbcnt_hi_u32_b32 v0, s7, v0
	v_cmp_eq_u32_e32 vcc, 0, v0
	s_waitcnt vmcnt(0)
	buffer_inv sc1
	s_and_saveexec_b64 s[8:9], vcc
	s_cbranch_execz .LBB0_1241
	s_bcnt1_i32_b64 s6, s[6:7]
	v_mov_b32_e32 v0, 0x2000
	v_mov_b32_e32 v1, s6
.LBB0_1241:
	s_or_b64 exec, exec, s[8:9]
	s_waitcnt vmcnt(0)

.LBB0_1304:
	s_or_b64 exec, exec, s[6:7]
	s_mov_b64 s[6:7], exec
	v_mbcnt_lo_u32_b32 v0, s6, 0
	v_mbcnt_hi_u32_b32 v0, s7, v0
	v_cmp_eq_u32_e32 vcc, 0, v0
	s_waitcnt vmcnt(0)
	buffer_inv sc1
	s_and_saveexec_b64 s[8:9], vcc
	s_cbranch_execz .LBB0_1306
	s_bcnt1_i32_b64 s6, s[6:7]
	v_mov_b32_e32 v0, 0x2000
	v_mov_b32_e32 v1, s6
.LBB0_1306:
	s_or_b64 exec, exec, s[8:9]
	s_waitcnt vmcnt(0)

.LBB0_1384:
	s_or_b64 exec, exec, s[4:5]
	s_mov_b64 s[4:5], exec
	v_mbcnt_lo_u32_b32 v0, s4, 0
	v_mbcnt_hi_u32_b32 v0, s5, v0
	v_cmp_eq_u32_e32 vcc, 0, v0
	s_waitcnt vmcnt(0)
	buffer_inv sc1
	s_and_saveexec_b64 s[8:9], vcc
	s_cbranch_execz .LBB0_1386
	s_bcnt1_i32_b64 s4, s[4:5]
	v_mov_b32_e32 v0, 0x2000
	v_mov_b32_e32 v1, s4
.LBB0_1386:
	s_or_b64 exec, exec, s[8:9]
	s_waitcnt vmcnt(0)

.LBB0_1513:
	s_or_b64 exec, exec, s[6:7]
	s_mov_b64 s[6:7], exec
	v_mbcnt_lo_u32_b32 v0, s6, 0
	v_mbcnt_hi_u32_b32 v0, s7, v0
	v_cmp_eq_u32_e32 vcc, 0, v0
	s_waitcnt vmcnt(0)
	buffer_inv sc1
	s_and_saveexec_b64 s[8:9], vcc
	s_cbranch_execz .LBB0_1515
	s_bcnt1_i32_b64 s6, s[6:7]
	v_mov_b32_e32 v0, 0x2000
	v_mov_b32_e32 v1, s6
.LBB0_1515:
	s_or_b64 exec, exec, s[8:9]
	s_waitcnt vmcnt(0)

.LBB0_1584:
	s_or_b64 exec, exec, s[4:5]
	s_mov_b64 s[4:5], exec
	v_mbcnt_lo_u32_b32 v0, s4, 0
	v_mbcnt_hi_u32_b32 v0, s5, v0
	v_cmp_eq_u32_e32 vcc, 0, v0
	s_waitcnt vmcnt(0)
	buffer_inv sc1
	s_and_saveexec_b64 s[6:7], vcc
	s_cbranch_execz .LBB0_1586
	s_bcnt1_i32_b64 s4, s[4:5]
	v_mov_b32_e32 v0, 0x2000
	v_mov_b32_e32 v1, s4
.LBB0_1586:
	s_or_b64 exec, exec, s[6:7]
	s_waitcnt vmcnt(0)

.LBB0_1661:
	s_or_b64 exec, exec, s[4:5]
	s_mov_b64 s[4:5], exec
	v_mbcnt_lo_u32_b32 v0, s4, 0
	v_mbcnt_hi_u32_b32 v0, s5, v0
	v_cmp_eq_u32_e32 vcc, 0, v0
	s_waitcnt vmcnt(0)
	buffer_inv sc1
	s_and_saveexec_b64 s[8:9], vcc
	s_cbranch_execz .LBB0_1663
	s_bcnt1_i32_b64 s4, s[4:5]
	v_mov_b32_e32 v0, 0x2000
	v_mov_b32_e32 v1, s4
.LBB0_1663:
	s_or_b64 exec, exec, s[8:9]
	s_waitcnt vmcnt(0)

.LBB0_1738:
	s_or_b64 exec, exec, s[6:7]
	s_mov_b64 s[6:7], exec
	v_mbcnt_lo_u32_b32 v0, s6, 0
	v_mbcnt_hi_u32_b32 v0, s7, v0
	v_cmp_eq_u32_e32 vcc, 0, v0
	s_waitcnt vmcnt(0)
	buffer_inv sc1
	s_and_saveexec_b64 s[8:9], vcc
	s_cbranch_execz .LBB0_1740
	s_bcnt1_i32_b64 s6, s[6:7]
	v_mov_b32_e32 v0, 0x2000
	v_mov_b32_e32 v1, s6
.LBB0_1740:
	s_or_b64 exec, exec, s[8:9]
	s_waitcnt vmcnt(0)

.LBB0_1935:
	s_or_b64 exec, exec, s[6:7]
	s_mov_b64 s[6:7], exec
	v_mbcnt_lo_u32_b32 v0, s6, 0
	v_mbcnt_hi_u32_b32 v0, s7, v0
	v_cmp_eq_u32_e32 vcc, 0, v0
	s_waitcnt vmcnt(0)
	buffer_inv sc1
	s_and_saveexec_b64 s[8:9], vcc
	s_cbranch_execz .LBB0_1937
	s_bcnt1_i32_b64 s6, s[6:7]
	v_mov_b32_e32 v0, 0x2000
	v_mov_b32_e32 v1, s6
.LBB0_1937:
	s_or_b64 exec, exec, s[8:9]
	s_waitcnt vmcnt(0)

.LBB0_2006:
	s_or_b64 exec, exec, s[6:7]
	s_mov_b64 s[6:7], exec
	v_mbcnt_lo_u32_b32 v0, s6, 0
	v_mbcnt_hi_u32_b32 v0, s7, v0
	v_cmp_eq_u32_e32 vcc, 0, v0
	s_waitcnt vmcnt(0)
	buffer_inv sc1
	s_and_saveexec_b64 s[8:9], vcc
	s_cbranch_execz .LBB0_2008
	s_bcnt1_i32_b64 s6, s[6:7]
	v_mov_b32_e32 v0, 0x2000
	v_mov_b32_e32 v1, s6
.LBB0_2008:
	s_or_b64 exec, exec, s[8:9]
	s_waitcnt vmcnt(0)

.LBB0_2123:
	s_or_b64 exec, exec, s[6:7]
	s_mov_b64 s[6:7], exec
	v_mbcnt_lo_u32_b32 v0, s6, 0
	v_mbcnt_hi_u32_b32 v0, s7, v0
	v_cmp_eq_u32_e32 vcc, 0, v0
	s_waitcnt vmcnt(0)
	buffer_inv sc1
	s_and_saveexec_b64 s[8:9], vcc
	s_cbranch_execz .LBB0_2125
	s_bcnt1_i32_b64 s6, s[6:7]
	v_mov_b32_e32 v0, 0x2000
	v_mov_b32_e32 v1, s6
.LBB0_2125:
	s_or_b64 exec, exec, s[8:9]
	s_waitcnt vmcnt(0)

.LBB0_2206:
	s_or_b64 exec, exec, s[4:5]
	s_mov_b64 s[4:5], exec
	v_mbcnt_lo_u32_b32 v0, s4, 0
	v_mbcnt_hi_u32_b32 v0, s5, v0
	v_cmp_eq_u32_e32 vcc, 0, v0
	s_waitcnt vmcnt(0)
	buffer_inv sc1
	s_and_saveexec_b64 s[8:9], vcc
	s_cbranch_execz .LBB0_2208
	s_bcnt1_i32_b64 s4, s[4:5]
	v_mov_b32_e32 v0, 0x2000
	v_mov_b32_e32 v1, s4
.LBB0_2208:
	s_or_b64 exec, exec, s[8:9]
	s_waitcnt vmcnt(0)

.LBB0_2277:
	s_or_b64 exec, exec, s[6:7]
	s_mov_b64 s[6:7], exec
	v_mbcnt_lo_u32_b32 v0, s6, 0
	v_mbcnt_hi_u32_b32 v0, s7, v0
	v_cmp_eq_u32_e32 vcc, 0, v0
	s_waitcnt vmcnt(0)
	buffer_inv sc1
	s_and_saveexec_b64 s[8:9], vcc
	s_cbranch_execz .LBB0_2279
	s_bcnt1_i32_b64 s6, s[6:7]
	v_mov_b32_e32 v0, 0x2000
	v_mov_b32_e32 v1, s6
.LBB0_2279:
	s_or_b64 exec, exec, s[8:9]
	s_waitcnt vmcnt(0)

.LBB0_2348:
	s_or_b64 exec, exec, s[6:7]
	s_mov_b64 s[6:7], exec
	v_mbcnt_lo_u32_b32 v0, s6, 0
	v_mbcnt_hi_u32_b32 v0, s7, v0
	v_cmp_eq_u32_e32 vcc, 0, v0
	s_waitcnt vmcnt(0)
	buffer_inv sc1
	s_and_saveexec_b64 s[8:9], vcc
	s_cbranch_execz .LBB0_2350
	s_bcnt1_i32_b64 s6, s[6:7]
	v_mov_b32_e32 v0, 0x2000
	v_mov_b32_e32 v1, s6
.LBB0_2350:
	s_or_b64 exec, exec, s[8:9]
	s_waitcnt vmcnt(0)

.LBB0_2413:
	s_or_b64 exec, exec, s[6:7]
	s_mov_b64 s[6:7], exec
	v_mbcnt_lo_u32_b32 v0, s6, 0
	v_mbcnt_hi_u32_b32 v0, s7, v0
	v_cmp_eq_u32_e32 vcc, 0, v0
	s_waitcnt vmcnt(0)
	buffer_inv sc1
	s_and_saveexec_b64 s[8:9], vcc
	s_cbranch_execz .LBB0_2415
	s_bcnt1_i32_b64 s6, s[6:7]
	v_mov_b32_e32 v0, 0x2000
	v_mov_b32_e32 v1, s6
.LBB0_2415:
	s_or_b64 exec, exec, s[8:9]
	s_waitcnt vmcnt(0)

.LBB0_2484:
	s_or_b64 exec, exec, s[6:7]
	s_mov_b64 s[6:7], exec
	v_mbcnt_lo_u32_b32 v0, s6, 0
	v_mbcnt_hi_u32_b32 v0, s7, v0
	v_cmp_eq_u32_e32 vcc, 0, v0
	s_waitcnt vmcnt(0)
	buffer_inv sc1
	s_and_saveexec_b64 s[8:9], vcc
	s_cbranch_execz .LBB0_2486
	s_bcnt1_i32_b64 s6, s[6:7]
	v_mov_b32_e32 v0, 0x2000
	v_mov_b32_e32 v1, s6
.LBB0_2486:
	s_or_b64 exec, exec, s[8:9]
	s_waitcnt vmcnt(0)

.LBB0_2549:
	s_or_b64 exec, exec, s[6:7]
	s_mov_b64 s[6:7], exec
	v_mbcnt_lo_u32_b32 v0, s6, 0
	v_mbcnt_hi_u32_b32 v0, s7, v0
	v_cmp_eq_u32_e32 vcc, 0, v0
	s_waitcnt vmcnt(0)
	buffer_inv sc1
	s_and_saveexec_b64 s[8:9], vcc
	s_cbranch_execz .LBB0_2551
	s_bcnt1_i32_b64 s6, s[6:7]
	v_mov_b32_e32 v0, 0x2000
	v_mov_b32_e32 v1, s6
.LBB0_2551:
	s_or_b64 exec, exec, s[8:9]
	s_waitcnt vmcnt(0)

.LBB0_2636:
	s_or_b64 exec, exec, s[4:5]
	s_mov_b64 s[4:5], exec
	v_mbcnt_lo_u32_b32 v0, s4, 0
	v_mbcnt_hi_u32_b32 v0, s5, v0
	v_cmp_eq_u32_e32 vcc, 0, v0
	s_waitcnt vmcnt(0)
	buffer_inv sc1
	s_and_saveexec_b64 s[6:7], vcc
	s_cbranch_execz .LBB0_2638
	s_bcnt1_i32_b64 s4, s[4:5]
	v_mov_b32_e32 v0, 0x2000
	v_mov_b32_e32 v1, s4
.LBB0_2638:
	s_or_b64 exec, exec, s[6:7]
	s_waitcnt vmcnt(0)
